# xcd barrier at the layer-0 seam; final phase row loads software-pipelined
# speedup vs baseline: 1.0396x; 1.0068x over previous
; __device__ __forceinline__ unsigned xb_add(unsigned* p, unsigned v) { return __hip_atomic_fetch_add(p, v, __ATOMIC_RELAXED, __HIP_MEMORY_SCOPE_AGENT); }
; __device__ __forceinline__ void xcd_barrier(const XcdBarrier& b) {
;     asm volatile("s_waitcnt vmcnt(0)" ::: "memory");
;     __syncthreads();
;     if (threadIdx.x == 0) {
;         unsigned* bar = b.bar;
;         __builtin_amdgcn_s_waitcnt(0);
;         unsigned nloc = b.st[0], nx = b.st[1];
;         if (nloc == 0u) { xcd_barrier_complete(bar, b.x, nloc, nx); b.st[0] = nloc; b.st[1] = nx; }
;         const unsigned old = xb_add(&bar[XB_XSUB(b.x)], 1u);
; __global__ void __launch_bounds__(512, 2) hymba_fwd(Args a) {
;     ...
;         if (layer == 0) grid.sync(); else xcd_barrier(bar);
.LBB0_146:
	s_waitcnt vmcnt(0)
	s_barrier
	s_mov_b64 s[4:5], exec
	v_readlane_b32 s0, v252, 6
	v_readlane_b32 s1, v252, 7
	s_and_b64 s[0:1], s[4:5], s[0:1]
	s_mov_b64 exec, s[0:1]
	s_cbranch_execz .LBB0_200
	v_readlane_b32 s0, v251, 18
	s_waitcnt vmcnt(0) expcnt(0) lgkmcnt(0)
	s_nop 0
	v_mov_b32_e32 v1, s0
	ds_read_b32 v3, v1
	v_readlane_b32 s0, v251, 19
	s_waitcnt lgkmcnt(0)
	v_cmp_ne_u32_e32 vcc, 0, v3
	v_mov_b32_e32 v1, s0
	ds_read_b32 v1, v1
	s_cbranch_vccnz .LBB0_164
	s_mov_b32 s0, 1
	s_branch .LBB0_151

; __device__ __forceinline__ int rfl(int v) { return __builtin_amdgcn_readfirstlane(v); }
; __device__ __forceinline__ int opaque_tid() { int t = threadIdx.x; asm volatile("" : "+v"(t)); return t; }
; __device__ __forceinline__ void final_phase(const Args& a) {
;     const int tid = opaque_tid(), lane = tid & 63, wid = rfl(tid >> 6);
;     const bf16_t* H = (const bf16_t*)(a.ws + WS_H); const bf16_t* Y = (const bf16_t*)(a.ws + WS_Y);
;     f32x4 g4[4];
; #pragma unroll
;     for (int jj = 0; jj < 4; ++jj) g4[jj] = *(const f32x4*)(a.final_gain + 256 * jj + 4 * lane);
;     for (int orow = blockIdx.x * 8 + wid; orow < NB * SEQ; orow += gridDim.x * 8) {
;         const int b = orow / SEQ, s = orow % SEQ; const size_t row = (size_t)b * LP + PADF + NMETA + s;
;         f32x4 v[4]; float ss = 0.f;
; #pragma unroll
;         for (int jj = 0; jj < 4; ++jj) { const u32x2 yb_ = *(const u32x2*)(Y + (size_t)orow * DM + 256 * jj + 4 * lane); const u32x2 hb_ = *(const u32x2*)(H + (size_t)orow * DM + 256 * jj + 4 * lane); v[jj] = (f32x4){__uint_as_float(hb_.x << 16), __uint_as_float(hb_.x & 0xffff0000u), __uint_as_float(hb_.y << 16), __uint_as_float(hb_.y & 0xffff0000u)} + (f32x4){__uint_as_float(yb_.x << 16), __uint_as_float(yb_.x & 0xffff0000u), __uint_as_float(yb_.y << 16), __uint_as_float(yb_.y & 0xffff0000u)}; ss += (v[jj].x * v[jj].x + v[jj].y * v[jj].y) + (v[jj].z * v[jj].z + v[jj].w * v[jj].w); }
.LBB0_725:
	v_readlane_b32 s1, v252, 8
	v_readfirstlane_b32 s0, v210
	s_ashr_i32 s0, s0, 6
	s_add_i32 s2, s0, s1
	s_cmpk_gt_i32 s2, 0x7fff
	s_cbranch_scc1 .LBB0_728
	v_readlane_b32 s8, v252, 2
	v_readlane_b32 s9, v252, 3
	s_load_dwordx2 s[0:1], s[8:9], 0x58
	s_load_dwordx4 s[4:7], s[8:9], 0x60
	v_lshlrev_b32_e32 v0, 2, v210
	v_and_b32_e32 v16, 0xfc, v0
	v_lshlrev_b32_e32 v20, 2, v16
	s_waitcnt lgkmcnt(0)
	global_load_dwordx4 v[0:3], v20, s[0:1]
	global_load_dwordx4 v[4:7], v20, s[0:1] offset:1024
	global_load_dwordx4 v[8:11], v20, s[0:1] offset:2048
	global_load_dwordx4 v[12:15], v20, s[0:1] offset:3072
	v_mov_b32_e32 v21, 0
	v_lshlrev_b32_e32 v16, 1, v16
	v_mov_b32_e32 v17, v21
	v_lshl_add_u64 v[18:19], s[6:7], 0, v[16:17]
	s_mov_b64 s[0:1], 0x13000000
	v_lshl_add_u64 v[16:17], v[18:19], 0, s[0:1]
	s_mov_b64 s[0:1], 0x2c00000
	v_lshl_add_u64 v[18:19], v[18:19], 0, s[0:1]
	v_lshl_add_u64 v[20:21], s[4:5], 0, v[20:21]
	v_mov_b32_e32 v22, 0x358637bd
	s_mov_b32 s4, 0xf800000
	v_mov_b32_e32 v23, 0x260
	v_readlane_b32 s5, v252, 9
	s_ashr_i32 s3, s2, 31
	s_lshl_b64 s[0:1], s[2:3], 11
	v_lshl_add_u64 v[76:77], v[18:19], 0, s[0:1]
	v_lshl_add_u64 v[78:79], v[16:17], 0, s[0:1]
	global_load_dwordx2 v[60:61], v[76:77], off
	global_load_dwordx2 v[62:63], v[78:79], off
	global_load_dwordx2 v[64:65], v[76:77], off offset:512
	global_load_dwordx2 v[66:67], v[78:79], off offset:512
	global_load_dwordx2 v[68:69], v[76:77], off offset:1024
	global_load_dwordx2 v[70:71], v[78:79], off offset:1024
	global_load_dwordx2 v[72:73], v[76:77], off offset:1536
	global_load_dwordx2 v[74:75], v[78:79], off offset:1536
	s_waitcnt vmcnt(0)
; __device__ __forceinline__ void final_phase(const Args& a) {
;     ...
;     for (int orow = blockIdx.x * 8 + wid; orow < NB * SEQ; orow += gridDim.x * 8) {
;         const int b = orow / SEQ, s = orow % SEQ; const size_t row = (size_t)b * LP + PADF + NMETA + s;
;         f32x4 v[4]; float ss = 0.f;
; #pragma unroll
;         for (int jj = 0; jj < 4; ++jj) { const u32x2 yb_ = *(const u32x2*)(Y + (size_t)orow * DM + 256 * jj + 4 * lane); const u32x2 hb_ = *(const u32x2*)(H + (size_t)orow * DM + 256 * jj + 4 * lane); v[jj] = (f32x4){__uint_as_float(hb_.x << 16), __uint_as_float(hb_.x & 0xffff0000u), __uint_as_float(hb_.y << 16), __uint_as_float(hb_.y & 0xffff0000u)} + (f32x4){__uint_as_float(yb_.x << 16), __uint_as_float(yb_.x & 0xffff0000u), __uint_as_float(yb_.y << 16), __uint_as_float(yb_.y & 0xffff0000u)}; ss += (v[jj].x * v[jj].x + v[jj].y * v[jj].y) + (v[jj].z * v[jj].z + v[jj].w * v[jj].w); }
;         ss = wsum(ss);
;         const float rstd = 1.0f / sqrtf(ss * (1.0f / DM) + 1e-6f);
; #pragma unroll
;         for (int jj = 0; jj < 4; ++jj) *(f32x4*)(a.out + (size_t)orow * DM + 256 * jj + 4 * lane) = v[jj] * rstd * g4[jj];
;     }
.LBB0_727:
	s_ashr_i32 s3, s2, 31
	s_lshl_b64 s[6:7], s[2:3], 12
	s_add_i32 s2, s2, s5
	s_waitcnt vmcnt(4)
	v_lshlrev_b32_e32 v28, 16, v62
	v_and_b32_e32 v29, 0xffff0000, v62
	v_lshlrev_b32_e32 v30, 16, v63
	v_and_b32_e32 v31, 0xffff0000, v63
	v_lshlrev_b32_e32 v24, 16, v60
	v_and_b32_e32 v25, 0xffff0000, v60
	v_lshlrev_b32_e32 v26, 16, v61
	v_and_b32_e32 v27, 0xffff0000, v61
	v_lshlrev_b32_e32 v44, 16, v64
	v_and_b32_e32 v45, 0xffff0000, v64
	v_lshlrev_b32_e32 v32, 16, v65
	v_and_b32_e32 v33, 0xffff0000, v65
	v_lshlrev_b32_e32 v46, 16, v66
	v_and_b32_e32 v47, 0xffff0000, v66
	v_lshlrev_b32_e32 v34, 16, v67
	v_and_b32_e32 v35, 0xffff0000, v67
	v_lshlrev_b32_e32 v48, 16, v68
	v_and_b32_e32 v49, 0xffff0000, v68
	v_lshlrev_b32_e32 v36, 16, v69
	v_and_b32_e32 v37, 0xffff0000, v69
	v_lshlrev_b32_e32 v50, 16, v70
	v_and_b32_e32 v51, 0xffff0000, v70
	v_lshlrev_b32_e32 v38, 16, v71
	v_and_b32_e32 v39, 0xffff0000, v71
	v_lshlrev_b32_e32 v52, 16, v72
	v_and_b32_e32 v53, 0xffff0000, v72
	v_lshlrev_b32_e32 v40, 16, v73
	v_and_b32_e32 v41, 0xffff0000, v73
	v_lshlrev_b32_e32 v54, 16, v74
	v_and_b32_e32 v55, 0xffff0000, v74
	v_lshlrev_b32_e32 v42, 16, v75
	v_and_b32_e32 v43, 0xffff0000, v75
	s_ashr_i32 s3, s2, 31
	s_lshl_b64 s[0:1], s[2:3], 11
	v_lshl_add_u64 v[76:77], v[18:19], 0, s[0:1]
	v_lshl_add_u64 v[78:79], v[16:17], 0, s[0:1]
	global_load_dwordx2 v[60:61], v[76:77], off
	global_load_dwordx2 v[62:63], v[78:79], off
	global_load_dwordx2 v[64:65], v[76:77], off offset:512
	global_load_dwordx2 v[66:67], v[78:79], off offset:512
	global_load_dwordx2 v[68:69], v[76:77], off offset:1024
	global_load_dwordx2 v[70:71], v[78:79], off offset:1024
	global_load_dwordx2 v[72:73], v[76:77], off offset:1536
	global_load_dwordx2 v[74:75], v[78:79], off offset:1536
	s_cmp_lt_i32 s2, 0x8000
	v_pk_add_f32 v[26:27], v[30:31], v[26:27]
	v_pk_add_f32 v[24:25], v[28:29], v[24:25]
	v_pk_add_f32 v[28:29], v[34:35], v[32:33]
	v_pk_add_f32 v[30:31], v[46:47], v[44:45]
	v_pk_add_f32 v[32:33], v[38:39], v[36:37]
	v_pk_add_f32 v[34:35], v[50:51], v[48:49]
	v_pk_add_f32 v[36:37], v[42:43], v[40:41]
	v_mul_f32_e32 v40, v25, v25
	v_mul_f32_e32 v41, v27, v27
	v_mul_f32_e32 v42, v31, v31
	v_mul_f32_e32 v43, v29, v29
	v_pk_add_f32 v[38:39], v[54:55], v[52:53]
	v_mul_f32_e32 v44, v35, v35
	v_mul_f32_e32 v45, v33, v33
	v_fmac_f32_e32 v40, v24, v24
	v_fmac_f32_e32 v41, v26, v26
	v_fmac_f32_e32 v42, v30, v30
	v_fmac_f32_e32 v43, v28, v28
	v_mul_f32_e32 v46, v39, v39
	v_mul_f32_e32 v47, v37, v37
	v_fmac_f32_e32 v44, v34, v34
	v_fmac_f32_e32 v45, v32, v32
	v_add_f32_e32 v40, v40, v41
	v_add_f32_e32 v41, v42, v43
	v_fmac_f32_e32 v46, v38, v38
	v_fmac_f32_e32 v47, v36, v36
	v_add_f32_e32 v42, v44, v45
	v_add_f32_e32 v40, v40, v41
	v_add_f32_e32 v43, v46, v47
	v_add_f32_e32 v40, v40, v42
	v_add_f32_e32 v40, v40, v43
	s_nop 1
	v_add_f32_dpp v40, v40, v40 quad_perm:[1,0,3,2] row_mask:0xf bank_mask:0xf bound_ctrl:1
	s_nop 1
	v_add_f32_dpp v40, v40, v40 quad_perm:[2,3,0,1] row_mask:0xf bank_mask:0xf bound_ctrl:1
	s_nop 1
	v_add_f32_dpp v40, v40, v40 row_half_mirror row_mask:0xf bank_mask:0xf bound_ctrl:1
	s_nop 1
	v_add_f32_dpp v40, v40, v40 row_mirror row_mask:0xf bank_mask:0xf bound_ctrl:1
	v_mov_b32_e32 v41, v40
	s_nop 1
	v_permlane16_swap_b32_e32 v40, v41
	v_add_f32_e32 v40, v40, v41
	v_mov_b32_e32 v41, v40
	s_nop 1
	v_permlane32_swap_b32_e32 v40, v41
	v_add_f32_e32 v40, v40, v41
	v_fmamk_f32 v40, v40, 0x3a800000, v22
	v_mul_f32_e32 v41, 0x4f800000, v40
	v_cmp_gt_f32_e32 vcc, s4, v40
	s_nop 1
	v_cndmask_b32_e32 v40, v40, v41, vcc
	v_sqrt_f32_e32 v41, v40
	s_nop 0
	v_add_u32_e32 v42, -1, v41
	v_add_u32_e32 v43, 1, v41
	v_fma_f32 v44, -v42, v41, v40
	v_fma_f32 v45, -v43, v41, v40
	v_cmp_ge_f32_e64 s[0:1], 0, v44
	s_nop 1
	v_cndmask_b32_e64 v41, v41, v42, s[0:1]
	v_cmp_lt_f32_e64 s[0:1], 0, v45
	s_nop 1
	v_cndmask_b32_e64 v41, v41, v43, s[0:1]
	v_mul_f32_e32 v42, 0x37800000, v41
	v_cndmask_b32_e32 v41, v41, v42, vcc
	v_cmp_class_f32_e32 vcc, v40, v23
	s_nop 1
	v_cndmask_b32_e32 v42, v41, v40, vcc
	v_div_scale_f32 v43, s[0:1], v42, v42, 1.0
	v_rcp_f32_e32 v44, v43
	v_div_scale_f32 v45, vcc, 1.0, v42, 1.0
	v_lshl_add_u64 v[40:41], v[20:21], 0, s[6:7]
	v_fma_f32 v46, -v43, v44, 1.0
	v_fmac_f32_e32 v44, v46, v44
	v_mul_f32_e32 v46, v45, v44
	v_fma_f32 v47, -v43, v46, v45
	v_fmac_f32_e32 v46, v47, v44
	v_fma_f32 v43, -v43, v46, v45
	v_div_fmas_f32 v43, v43, v44, v46
	v_div_fixup_f32 v42, v43, v42, 1.0
	v_pk_mul_f32 v[24:25], v[24:25], v[42:43] op_sel_hi:[1,0]
	v_pk_mul_f32 v[26:27], v[26:27], v[42:43] op_sel_hi:[1,0]
	v_pk_mul_f32 v[44:45], v[30:31], v[42:43] op_sel_hi:[1,0]
	v_pk_mul_f32 v[28:29], v[28:29], v[42:43] op_sel_hi:[1,0]
	v_pk_mul_f32 v[26:27], v[2:3], v[26:27]
	v_pk_mul_f32 v[24:25], v[0:1], v[24:25]
	v_pk_mul_f32 v[34:35], v[34:35], v[42:43] op_sel_hi:[1,0]
	v_pk_mul_f32 v[30:31], v[6:7], v[28:29]
	v_pk_mul_f32 v[28:29], v[4:5], v[44:45]
	global_store_dwordx4 v[40:41], v[24:27], off
	global_store_dwordx4 v[40:41], v[28:31], off offset:1024
	s_nop 0
	v_pk_mul_f32 v[24:25], v[32:33], v[42:43] op_sel_hi:[1,0]
	s_nop 0
	v_pk_mul_f32 v[26:27], v[10:11], v[24:25]
	v_pk_mul_f32 v[24:25], v[8:9], v[34:35]
	global_store_dwordx4 v[40:41], v[24:27], off offset:2048
	s_nop 1
	v_pk_mul_f32 v[24:25], v[38:39], v[42:43] op_sel_hi:[1,0]
	v_pk_mul_f32 v[26:27], v[36:37], v[42:43] op_sel_hi:[1,0]
	v_pk_mul_f32 v[24:25], v[12:13], v[24:25]
	v_pk_mul_f32 v[26:27], v[14:15], v[26:27]
	global_store_dwordx4 v[40:41], v[24:27], off offset:3072
	s_cbranch_scc1 .LBB0_727
